# samp_hg: small bf16 loads issued first in distinct registers, state prefetch of next unit stays in flight (vmcnt(34) instead of 3x vmcnt(0)), on top of v2
# speedup vs baseline: 1.0015x; 1.0015x over previous
.LBB0_560:
	s_add_i32 s1, s9, s11
	s_and_b32 s8, s1, 0x1ff
	s_or_b32 s12, s52, s8
	s_mov_b32 s13, s53
	s_lshl_b64 s[12:13], s[12:13], 16
	v_lshl_add_u64 v[24:25], v[64:65], 0, s[12:13]
	v_readlane_b32 s14, v251, 41
	s_and_b32 s12, s9, 3
	v_readlane_b32 s15, v251, 42
	s_lshl_b32 s13, s12, 7
	s_andn2_b64 vcc, exec, s[14:15]
	v_mov_b32_e32 v76, 0
	s_cbranch_vccnz .LBB0_562
	v_or_b32_e32 v74, s13, v69
	v_lshlrev_b32_e32 v74, 2, v74
	v_mov_b32_e32 v75, v209
	v_lshl_add_u64 v[74:75], s[2:3], 0, v[74:75]
	v_add_co_u32_e32 v74, vcc, 0x101000, v74
	s_nop 1
	v_addc_co_u32_e32 v75, vcc, 0, v75, vcc
	global_load_dword v76, v[74:75], off
.LBB0_562:
	s_ashr_i32 s8, s9, 2
	s_and_b32 s9, s9, -4
	v_add_u32_e32 v74, s9, v83
	v_mov_b64_e32 v[78:79], s[4:5]
	v_mad_i64_i32 v[78:79], s[14:15], v74, s89, v[78:79]
	s_lshl_b32 s54, s13, 1
	v_lshl_add_u64 v[78:79], v[78:79], 0, s[54:55]
	v_lshl_add_u64 v[78:79], v[78:79], 0, v[208:209]
	global_load_ushort v198, v[78:79], off offset:2048
	s_movk_i32 s13, 0x1000
	s_ashr_i32 s9, s8, 31
	s_lshl_b64 s[8:9], s[8:9], 2
	s_add_u32 s8, s8, s52
	s_addc_u32 s9, s9, s53
	s_or_b32 s8, s8, s12
	s_lshl_b64 s[8:9], s[8:9], 16
	global_load_ushort v199, v[78:79], off offset:1024
	global_load_ushort v200, v[78:79], off offset:3072
	v_add_co_u32_e32 v78, vcc, s13, v78
	s_nop 1
	v_addc_co_u32_e32 v79, vcc, 0, v79, vcc
	global_load_ushort v75, v[78:79], off
	global_load_dword v77, v[66:67], off
	s_movk_i32 s98, 0x1000
	v_add_co_u32_e32 v16, vcc, s98, v24
	global_load_dword v0, v[24:25], off
	global_load_dword v1, v[24:25], off offset:512
	global_load_dword v2, v[24:25], off offset:1024
	global_load_dword v3, v[24:25], off offset:1536
	global_load_dword v4, v[24:25], off offset:2048
	global_load_dword v5, v[24:25], off offset:2560
	global_load_dword v6, v[24:25], off offset:3072
	global_load_dword v7, v[24:25], off offset:3584
	v_addc_co_u32_e32 v17, vcc, 0, v25, vcc
	v_add_co_u32_e32 v26, vcc, s70, v24
	s_movk_i32 s98, 0x3000
	s_nop 0
	v_addc_co_u32_e32 v27, vcc, 0, v25, vcc
	global_load_dword v8, v[26:27], off offset:-4096
	global_load_dword v9, v[16:17], off offset:512
	global_load_dword v10, v[16:17], off offset:1024
	global_load_dword v11, v[16:17], off offset:1536
	global_load_dword v12, v[16:17], off offset:2048
	global_load_dword v13, v[16:17], off offset:2560
	global_load_dword v14, v[16:17], off offset:3072
	global_load_dword v15, v[16:17], off offset:3584
	s_nop 0
	global_load_dword v16, v[26:27], off
	global_load_dword v17, v[26:27], off offset:512
	global_load_dword v18, v[26:27], off offset:1024
	global_load_dword v19, v[26:27], off offset:1536
	global_load_dword v20, v[26:27], off offset:2048
	global_load_dword v21, v[26:27], off offset:2560
	global_load_dword v22, v[26:27], off offset:3072
	global_load_dword v23, v[26:27], off offset:3584
	v_add_co_u32_e32 v210, vcc, s98, v24
	s_nop 1
	v_addc_co_u32_e32 v211, vcc, 0, v25, vcc
	global_load_dword v24, v[210:211], off
	global_load_dword v25, v[210:211], off offset:512
	global_load_dword v26, v[210:211], off offset:1024
	global_load_dword v27, v[210:211], off offset:1536
	global_load_dword v28, v[210:211], off offset:2048
	global_load_dword v29, v[210:211], off offset:2560
	global_load_dword v30, v[210:211], off offset:3072
	global_load_dword v31, v[210:211], off offset:3584
	s_waitcnt vmcnt(34)
	v_lshlrev_b32_e32 v87, 16, v198
	v_lshlrev_b32_e32 v88, 16, v199
	v_lshlrev_b32_e32 v89, 16, v200
	v_mul_f32_e32 v78, 0xbfb8aa3b, v87
	v_exp_f32_e32 v78, v78
	v_sub_f32_e32 v87, 1.0, v76
	s_barrier
	v_add_f32_e32 v79, 1.0, v78
	v_rcp_f32_e32 v79, v79
	v_mul_f32_e32 v78, v87, v78
	v_fmac_f32_e32 v76, v87, v79
	v_mul_f32_e32 v78, v78, v79
	ds_write2st64_b32 v84, v76, v78 offset1:8
	ds_write2st64_b32 v84, v88, v89 offset0:16 offset1:24
	s_waitcnt lgkmcnt(0)
	s_barrier
	ds_read2st64_b32 v[78:79], v82 offset0:24 offset1:26
	ds_read_b128 v[88:91], v68
	ds_read_b128 v[100:103], v68 offset:16
	ds_read_b128 v[104:107], v68 offset:32
	ds_read_b128 v[108:111], v68 offset:48
	ds_read_b128 v[92:95], v68 offset:2048
	ds_read_b128 v[112:115], v68 offset:4096
	s_waitcnt lgkmcnt(1)
	v_mul_f32_e32 v98, v78, v92
	v_mul_f32_e32 v92, v78, v93
	v_mul_f32_e32 v93, v78, v94
	v_mul_f32_e32 v94, v78, v95
	v_fmac_f32_e32 v98, v32, v88
	v_fmac_f32_e32 v92, v33, v89
	v_fmac_f32_e32 v93, v34, v90
	v_fmac_f32_e32 v94, v35, v91
	ds_read_b128 v[88:91], v68 offset:2064
	s_waitcnt lgkmcnt(1)
	v_fma_f32 v32, v112, v98, 0
	v_fmac_f32_e32 v32, v113, v92
	v_fmac_f32_e32 v32, v114, v93
	v_fmac_f32_e32 v32, v115, v94
	ds_read_b128 v[112:115], v68 offset:4112
	s_waitcnt lgkmcnt(1)
	v_mul_f32_e32 v97, v78, v88
	v_mul_f32_e32 v88, v78, v89
	v_fmac_f32_e32 v97, v36, v100
	v_fmac_f32_e32 v88, v37, v101
	ds_read_b128 v[34:37], v68 offset:2080
	v_mul_f32_e32 v87, v78, v90
	v_mul_f32_e32 v76, v78, v91
	v_fmac_f32_e32 v87, v38, v102
	v_fmac_f32_e32 v76, v39, v103
	ds_read_b128 v[100:103], v68 offset:4128
	s_waitcnt lgkmcnt(2)
	v_fmac_f32_e32 v32, v112, v97
	v_fmac_f32_e32 v32, v113, v88
	v_fmac_f32_e32 v32, v114, v87
	s_waitcnt lgkmcnt(1)
	v_mul_f32_e32 v96, v78, v34
	v_fmac_f32_e32 v32, v115, v76
	v_fmac_f32_e32 v96, v40, v104
	v_mul_f32_e32 v89, v78, v35
	v_fmac_f32_e32 v89, v41, v105
	v_mul_f32_e32 v90, v78, v36
	ds_read_b128 v[38:41], v68 offset:2096
	s_waitcnt lgkmcnt(1)
	v_fmac_f32_e32 v32, v100, v96
	v_fmac_f32_e32 v32, v101, v89
	v_fmac_f32_e32 v90, v42, v106
	v_mul_f32_e32 v91, v78, v37
	v_fmac_f32_e32 v32, v102, v90
	v_fmac_f32_e32 v91, v43, v107
	v_fmac_f32_e32 v32, v103, v91
	ds_read_b128 v[100:103], v68 offset:4144
	s_waitcnt lgkmcnt(1)
	v_mul_f32_e32 v95, v78, v38
	v_fmac_f32_e32 v95, v44, v108
	v_mul_f32_e32 v38, v78, v39
	v_fmac_f32_e32 v38, v45, v109
	s_waitcnt lgkmcnt(0)
	v_fmac_f32_e32 v32, v100, v95
	v_mul_f32_e32 v37, v78, v40
	v_mul_f32_e32 v36, v78, v41
	v_fmac_f32_e32 v32, v101, v38
	v_fmac_f32_e32 v37, v46, v110
	v_fmac_f32_e32 v36, v47, v111
	ds_read_b128 v[40:43], v68 offset:64
	ds_read_b128 v[44:47], v68 offset:2112
	v_fmac_f32_e32 v32, v102, v37
	v_fmac_f32_e32 v32, v103, v36
	ds_read_b128 v[100:103], v68 offset:4160
	s_waitcnt lgkmcnt(1)
	v_mul_f32_e32 v44, v78, v44
	v_fmac_f32_e32 v44, v48, v40
	v_mul_f32_e32 v39, v78, v45
	s_waitcnt lgkmcnt(0)
	v_fmac_f32_e32 v32, v100, v44
	v_fmac_f32_e32 v39, v49, v41
	v_mul_f32_e32 v40, v78, v46
	v_fmac_f32_e32 v32, v101, v39
	v_fmac_f32_e32 v40, v50, v42
	v_mul_f32_e32 v41, v78, v47
	v_fmac_f32_e32 v32, v102, v40
	v_fmac_f32_e32 v41, v51, v43
	v_fmac_f32_e32 v32, v103, v41
	ds_read_b128 v[46:49], v68 offset:80
	ds_read_b128 v[100:103], v68 offset:2128
	ds_read_b128 v[104:107], v68 offset:4176
	s_waitcnt lgkmcnt(1)
	v_mul_f32_e32 v45, v78, v100
	v_fmac_f32_e32 v45, v52, v46
	v_mul_f32_e32 v42, v78, v101
	v_mul_f32_e32 v43, v78, v102
	v_mul_f32_e32 v46, v78, v103
	v_fmac_f32_e32 v42, v53, v47
	v_fmac_f32_e32 v43, v54, v48
	v_fmac_f32_e32 v46, v55, v49
	ds_read_b128 v[48:51], v68 offset:96
	ds_read_b128 v[52:55], v68 offset:2144
	ds_read_b128 v[100:103], v68 offset:4192
	s_waitcnt lgkmcnt(3)
	v_fmac_f32_e32 v32, v104, v45
	v_fmac_f32_e32 v32, v105, v42
	v_fmac_f32_e32 v32, v106, v43
	s_waitcnt lgkmcnt(1)
	v_mul_f32_e32 v47, v78, v52
	v_fmac_f32_e32 v32, v107, v46
	v_fmac_f32_e32 v47, v56, v48
	v_mul_f32_e32 v99, v78, v53
	s_waitcnt lgkmcnt(0)
	v_fmac_f32_e32 v32, v100, v47
	v_fmac_f32_e32 v99, v57, v49
	v_fmac_f32_e32 v32, v101, v99
	v_mul_f32_e32 v100, v78, v54
	v_mul_f32_e32 v101, v78, v55
	v_fmac_f32_e32 v100, v58, v50
	v_fmac_f32_e32 v101, v59, v51
	ds_read_b128 v[52:55], v68 offset:112
	ds_read_b128 v[56:59], v68 offset:2160
	ds_read_b128 v[104:107], v68 offset:4208
	v_fmac_f32_e32 v32, v102, v100
	v_fmac_f32_e32 v32, v103, v101
	s_waitcnt lgkmcnt(1)
	v_mul_f32_e32 v102, v78, v56
	v_fmac_f32_e32 v102, v60, v52
	v_mul_f32_e32 v51, v78, v57
	s_waitcnt lgkmcnt(0)
	v_fmac_f32_e32 v32, v104, v102
	v_fmac_f32_e32 v51, v61, v53
	v_mul_f32_e32 v52, v78, v58
	v_fmac_f32_e32 v32, v105, v51
	v_fmac_f32_e32 v52, v62, v54
	v_mul_f32_e32 v53, v78, v59
	v_fmac_f32_e32 v32, v106, v52
	v_fmac_f32_e32 v53, v63, v55
	v_fmac_f32_e32 v32, v107, v53
	ds_write_b32 v86, v32 offset:8192
	ds_read_b128 v[56:59], v68 offset:512
	ds_read_b128 v[60:63], v68 offset:528
	ds_read_b128 v[104:107], v68 offset:544
	ds_read_b128 v[32:35], v68 offset:560
	ds_read_b128 v[108:111], v68 offset:2560
	ds_read_b128 v[112:115], v68 offset:4608
	s_waitcnt lgkmcnt(1)
	v_mul_f32_e32 v54, v79, v108
	v_mul_f32_e32 v55, v79, v109
	v_fmac_f32_e32 v54, v98, v56
	v_fmac_f32_e32 v55, v92, v57
	v_mul_f32_e32 v56, v79, v110
	v_mul_f32_e32 v57, v79, v111
	ds_read_b128 v[108:111], v68 offset:2576
	s_waitcnt lgkmcnt(1)
	v_fma_f32 v98, v112, v54, 0
	v_fmac_f32_e32 v98, v113, v55
	v_fmac_f32_e32 v56, v93, v58
	v_fmac_f32_e32 v98, v114, v56
	v_fmac_f32_e32 v57, v94, v59
	s_waitcnt lgkmcnt(0)
	v_mul_f32_e32 v58, v79, v108
	v_mul_f32_e32 v48, v79, v109
	v_mul_f32_e32 v49, v79, v110
	v_mul_f32_e32 v59, v79, v111
	v_fmac_f32_e32 v98, v115, v57
	v_fmac_f32_e32 v58, v97, v60
	ds_read_b128 v[112:115], v68 offset:4624
	v_fmac_f32_e32 v48, v88, v61
	v_fmac_f32_e32 v49, v87, v62
	v_fmac_f32_e32 v59, v76, v63
	ds_read_b128 v[60:63], v68 offset:2592
	ds_read_b128 v[108:111], v68 offset:4640
	s_waitcnt lgkmcnt(2)
	v_fmac_f32_e32 v98, v112, v58
	v_fmac_f32_e32 v98, v113, v48
	v_fmac_f32_e32 v98, v114, v49
	s_waitcnt lgkmcnt(1)
	v_mul_f32_e32 v61, v79, v61
	v_mul_f32_e32 v62, v79, v62
	v_mul_f32_e32 v63, v79, v63
	v_fmac_f32_e32 v61, v89, v105
	v_fmac_f32_e32 v62, v90, v106
	v_fmac_f32_e32 v63, v91, v107
	ds_read_b128 v[88:91], v68 offset:2608
	v_mul_f32_e32 v60, v79, v60
	v_fmac_f32_e32 v98, v115, v59
	v_fmac_f32_e32 v60, v96, v104
	s_waitcnt lgkmcnt(1)
	v_fmac_f32_e32 v98, v108, v60
	s_waitcnt lgkmcnt(0)
	v_mul_f32_e32 v76, v79, v88
	v_fmac_f32_e32 v76, v95, v32
	ds_read_b128 v[92:95], v68 offset:4656
	v_fmac_f32_e32 v98, v109, v61
	v_fmac_f32_e32 v98, v110, v62
	v_fmac_f32_e32 v98, v111, v63
	v_mul_f32_e32 v50, v79, v89
	s_waitcnt lgkmcnt(0)
	v_fmac_f32_e32 v98, v92, v76
	v_fmac_f32_e32 v50, v38, v33
	v_mul_f32_e32 v38, v79, v90
	v_mul_f32_e32 v78, v79, v91
	v_fmac_f32_e32 v98, v93, v50
	v_fmac_f32_e32 v38, v37, v34
	v_fmac_f32_e32 v78, v36, v35
	ds_read_b128 v[32:35], v68 offset:576
	ds_read_b128 v[88:91], v68 offset:2624
	v_fmac_f32_e32 v98, v94, v38
	v_fmac_f32_e32 v98, v95, v78
	ds_read_b128 v[92:95], v68 offset:4672
	s_waitcnt lgkmcnt(1)
	v_mul_f32_e32 v87, v79, v88
	v_fmac_f32_e32 v87, v44, v32
	v_mul_f32_e32 v44, v79, v89
	s_waitcnt lgkmcnt(0)
	v_fmac_f32_e32 v98, v92, v87
	v_fmac_f32_e32 v44, v39, v33
	v_mul_f32_e32 v88, v79, v90
	v_mul_f32_e32 v89, v79, v91
	v_fmac_f32_e32 v98, v93, v44
	v_fmac_f32_e32 v88, v40, v34
	v_fmac_f32_e32 v89, v41, v35
	ds_read_b128 v[32:35], v68 offset:592
	ds_read_b128 v[90:93], v68 offset:2640
	v_fmac_f32_e32 v98, v94, v88
	v_fmac_f32_e32 v98, v95, v89
	ds_read_b128 v[94:97], v68 offset:4688
	s_waitcnt lgkmcnt(1)
	v_mul_f32_e32 v90, v79, v90
	v_fmac_f32_e32 v90, v45, v32
	v_mul_f32_e32 v39, v79, v91
	s_waitcnt lgkmcnt(0)
	v_fmac_f32_e32 v98, v94, v90
	v_fmac_f32_e32 v39, v42, v33
	v_mul_f32_e32 v40, v79, v92
	v_mul_f32_e32 v45, v79, v93
	v_fmac_f32_e32 v98, v95, v39
	v_fmac_f32_e32 v40, v43, v34
	v_fmac_f32_e32 v45, v46, v35
	ds_read_b128 v[32:35], v68 offset:608
	ds_read_b128 v[92:95], v68 offset:2656
	v_fmac_f32_e32 v98, v96, v40
	v_fmac_f32_e32 v98, v97, v45
	ds_read_b128 v[104:107], v68 offset:4704
	s_waitcnt lgkmcnt(1)
	v_mul_f32_e32 v46, v79, v92
	v_fmac_f32_e32 v46, v47, v32
	v_mul_f32_e32 v47, v79, v93
	v_mul_f32_e32 v91, v79, v94
	v_mul_f32_e32 v92, v79, v95
	v_fmac_f32_e32 v47, v99, v33
	v_fmac_f32_e32 v91, v100, v34
	v_fmac_f32_e32 v92, v101, v35
	ds_read_b128 v[32:35], v68 offset:624
	ds_read_b128 v[94:97], v68 offset:2672
	s_waitcnt lgkmcnt(2)
	v_fmac_f32_e32 v98, v104, v46
	v_fmac_f32_e32 v98, v105, v47
	v_fmac_f32_e32 v98, v106, v91
	v_fmac_f32_e32 v98, v107, v92
	s_waitcnt lgkmcnt(0)
	v_mul_f32_e32 v93, v79, v94
	v_fmac_f32_e32 v93, v102, v32
	ds_read_b128 v[100:103], v68 offset:4720
	v_mul_f32_e32 v41, v79, v95
	v_fmac_f32_e32 v41, v51, v33
	v_mul_f32_e32 v42, v79, v96
	v_fmac_f32_e32 v42, v52, v34
	s_waitcnt lgkmcnt(0)
	v_fmac_f32_e32 v98, v100, v93
	v_fmac_f32_e32 v98, v101, v41
	v_mul_f32_e32 v43, v79, v97
	v_fmac_f32_e32 v98, v102, v42
	v_fmac_f32_e32 v43, v53, v35
	v_fmac_f32_e32 v98, v103, v43
	ds_write_b32 v86, v98 offset:8704
	ds_read2st64_b32 v[36:37], v82 offset0:28 offset1:30
	ds_read_b128 v[94:97], v68 offset:1024
	ds_read_b128 v[98:101], v68 offset:1040
	ds_read_b128 v[102:105], v68 offset:1056
	ds_read_b128 v[32:35], v68 offset:1072
	ds_read_b128 v[106:109], v68 offset:3072
	ds_read_b128 v[110:113], v68 offset:5120
	s_waitcnt lgkmcnt(1)
	v_mul_f32_e32 v52, v36, v106
	v_mul_f32_e32 v53, v36, v107
	v_fmac_f32_e32 v52, v54, v94
	v_fmac_f32_e32 v53, v55, v95
	v_mul_f32_e32 v54, v36, v108
	v_mul_f32_e32 v55, v36, v109
	ds_read_b128 v[106:109], v68 offset:3088
	s_waitcnt lgkmcnt(1)
	v_fma_f32 v94, v110, v52, 0
	v_fmac_f32_e32 v94, v111, v53
	v_fmac_f32_e32 v54, v56, v96
	v_fmac_f32_e32 v94, v112, v54
	v_fmac_f32_e32 v55, v57, v97
	s_waitcnt lgkmcnt(0)
	v_mul_f32_e32 v56, v36, v106
	v_mul_f32_e32 v51, v36, v107
	v_fmac_f32_e32 v94, v113, v55
	v_fmac_f32_e32 v56, v58, v98
	ds_read_b128 v[110:113], v68 offset:5136
	v_fmac_f32_e32 v51, v48, v99
	ds_read_b128 v[96:99], v68 offset:3104
	v_mul_f32_e32 v48, v36, v108
	v_mul_f32_e32 v57, v36, v109
	ds_read_b128 v[106:109], v68 offset:5152
	s_waitcnt lgkmcnt(2)
	v_fmac_f32_e32 v94, v110, v56
	v_fmac_f32_e32 v57, v59, v101
	s_waitcnt lgkmcnt(1)
	v_mul_f32_e32 v58, v36, v96
	v_mul_f32_e32 v59, v36, v97
	v_fmac_f32_e32 v94, v111, v51
	v_fmac_f32_e32 v48, v49, v100
	v_fmac_f32_e32 v58, v60, v102
	v_fmac_f32_e32 v59, v61, v103
	v_mul_f32_e32 v60, v36, v98
	v_mul_f32_e32 v61, v36, v99
	ds_read_b128 v[96:99], v68 offset:3120
	v_fmac_f32_e32 v94, v112, v48
	v_fmac_f32_e32 v94, v113, v57
	ds_read_b128 v[100:103], v68 offset:5168
	s_waitcnt lgkmcnt(2)
	v_fmac_f32_e32 v94, v106, v58
	v_fmac_f32_e32 v94, v107, v59
	v_fmac_f32_e32 v60, v62, v104
	v_fmac_f32_e32 v94, v108, v60
	v_fmac_f32_e32 v61, v63, v105
	s_waitcnt lgkmcnt(1)
	v_mul_f32_e32 v62, v36, v96
	v_fmac_f32_e32 v94, v109, v61
	v_fmac_f32_e32 v62, v76, v32
	v_mul_f32_e32 v49, v36, v97
	s_waitcnt lgkmcnt(0)
	v_fmac_f32_e32 v94, v100, v62
	v_fmac_f32_e32 v49, v50, v33
	v_mul_f32_e32 v50, v36, v98
	v_mul_f32_e32 v63, v36, v99
	v_fmac_f32_e32 v94, v101, v49
	v_fmac_f32_e32 v50, v38, v34
	v_fmac_f32_e32 v63, v78, v35
	ds_read_b128 v[32:35], v68 offset:1088
	ds_read_b128 v[96:99], v68 offset:3136
	v_fmac_f32_e32 v94, v102, v50
	v_fmac_f32_e32 v94, v103, v63
	ds_read_b128 v[100:103], v68 offset:5184
	s_waitcnt lgkmcnt(1)
	v_mul_f32_e32 v76, v36, v96
	v_fmac_f32_e32 v76, v87, v32
	v_mul_f32_e32 v78, v36, v97
	s_waitcnt lgkmcnt(0)
	v_fmac_f32_e32 v94, v100, v76
	v_fmac_f32_e32 v78, v44, v33
	v_mul_f32_e32 v44, v36, v98
	v_mul_f32_e32 v79, v36, v99
	v_fmac_f32_e32 v94, v101, v78
	v_fmac_f32_e32 v44, v88, v34
	v_fmac_f32_e32 v79, v89, v35
	ds_read_b128 v[32:35], v68 offset:1104
	ds_read_b128 v[96:99], v68 offset:3152
	v_fmac_f32_e32 v94, v102, v44
	v_fmac_f32_e32 v94, v103, v79
	ds_read_b128 v[100:103], v68 offset:5200
	s_waitcnt lgkmcnt(1)
	v_mul_f32_e32 v87, v36, v96
	v_fmac_f32_e32 v87, v90, v32
	v_mul_f32_e32 v38, v36, v97
	s_waitcnt lgkmcnt(0)
	v_fmac_f32_e32 v94, v100, v87
	v_fmac_f32_e32 v38, v39, v33
	v_mul_f32_e32 v39, v36, v98
	v_mul_f32_e32 v88, v36, v99
	v_fmac_f32_e32 v94, v101, v38
	v_fmac_f32_e32 v39, v40, v34
	v_fmac_f32_e32 v88, v45, v35
	ds_read_b128 v[32:35], v68 offset:1120
	ds_read_b128 v[96:99], v68 offset:3168
	v_fmac_f32_e32 v94, v102, v39
	v_fmac_f32_e32 v94, v103, v88
	ds_read_b128 v[100:103], v68 offset:5216
	s_waitcnt lgkmcnt(1)
	v_mul_f32_e32 v45, v36, v96
	v_fmac_f32_e32 v45, v46, v32
	v_mul_f32_e32 v46, v36, v97
	s_waitcnt lgkmcnt(0)
	v_fmac_f32_e32 v94, v100, v45
	v_fmac_f32_e32 v46, v47, v33
	v_mul_f32_e32 v47, v36, v98
	v_mul_f32_e32 v89, v36, v99
	v_fmac_f32_e32 v94, v101, v46
	v_fmac_f32_e32 v47, v91, v34
	v_fmac_f32_e32 v89, v92, v35
	ds_read_b128 v[32:35], v68 offset:1136
	ds_read_b128 v[96:99], v68 offset:3184
	v_fmac_f32_e32 v94, v102, v47
	v_fmac_f32_e32 v94, v103, v89
	ds_read_b128 v[100:103], v68 offset:5232
	s_waitcnt lgkmcnt(1)
	v_mul_f32_e32 v90, v36, v96
	v_fmac_f32_e32 v90, v93, v32
	v_mul_f32_e32 v40, v36, v97
	s_waitcnt lgkmcnt(0)
	v_fmac_f32_e32 v94, v100, v90
	v_fmac_f32_e32 v40, v41, v33
	v_mul_f32_e32 v41, v36, v98
	v_fmac_f32_e32 v94, v101, v40
	v_fmac_f32_e32 v41, v42, v34
	v_mul_f32_e32 v36, v36, v99
	v_fmac_f32_e32 v94, v102, v41
	v_fmac_f32_e32 v36, v43, v35
	v_fmac_f32_e32 v94, v103, v36
	ds_write_b32 v86, v94 offset:9216
	ds_read_b128 v[92:95], v68 offset:1536
	ds_read_b128 v[96:99], v68 offset:1552
	ds_read_b128 v[100:103], v68 offset:1568
	ds_read_b128 v[32:35], v68 offset:1584
	ds_read_b128 v[104:107], v68 offset:3584
	ds_read_b128 v[108:111], v68 offset:5632
	s_waitcnt lgkmcnt(1)
	v_mul_f32_e32 v42, v37, v104
	v_mul_f32_e32 v43, v37, v105
	v_fmac_f32_e32 v42, v52, v92
	v_fmac_f32_e32 v43, v53, v93
	v_mul_f32_e32 v52, v37, v106
	v_mul_f32_e32 v53, v37, v107
	v_fmac_f32_e32 v52, v54, v94
	v_fmac_f32_e32 v53, v55, v95
	ds_read_b128 v[92:95], v68 offset:3600
	ds_read_b128 v[104:107], v68 offset:5648
	s_waitcnt lgkmcnt(2)
	v_fma_f32 v91, v108, v42, 0
	v_fmac_f32_e32 v91, v109, v43
	v_fmac_f32_e32 v91, v110, v52
	s_waitcnt lgkmcnt(1)
	v_mul_f32_e32 v55, v37, v93
	v_fmac_f32_e32 v55, v51, v97
	v_mul_f32_e32 v51, v37, v94
	v_mul_f32_e32 v54, v37, v92
	v_fmac_f32_e32 v51, v48, v98
	v_mul_f32_e32 v48, v37, v95
	ds_read_b128 v[92:95], v68 offset:3616
	v_fmac_f32_e32 v91, v111, v53
	v_fmac_f32_e32 v54, v56, v96
	v_fmac_f32_e32 v48, v57, v99
	ds_read_b128 v[96:99], v68 offset:5664
	s_waitcnt lgkmcnt(2)
	v_fmac_f32_e32 v91, v104, v54
	v_fmac_f32_e32 v91, v105, v55
	v_fmac_f32_e32 v91, v106, v51
	s_waitcnt lgkmcnt(1)
	v_mul_f32_e32 v56, v37, v92
	v_fmac_f32_e32 v91, v107, v48
	v_fmac_f32_e32 v56, v58, v100
	v_mul_f32_e32 v57, v37, v93
	s_waitcnt lgkmcnt(0)
	v_fmac_f32_e32 v91, v96, v56
	v_fmac_f32_e32 v57, v59, v101
	v_fmac_f32_e32 v91, v97, v57
	v_mul_f32_e32 v96, v37, v94
	v_mul_f32_e32 v97, v37, v95
	v_fmac_f32_e32 v96, v60, v102
	v_fmac_f32_e32 v97, v61, v103
	ds_read_b128 v[58:61], v68 offset:3632
	ds_read_b128 v[92:95], v68 offset:5680
	v_fmac_f32_e32 v91, v98, v96
	v_fmac_f32_e32 v91, v99, v97
	s_waitcnt lgkmcnt(1)
	v_mul_f32_e32 v98, v37, v58
	v_fmac_f32_e32 v98, v62, v32
	v_mul_f32_e32 v62, v37, v59
	v_fmac_f32_e32 v62, v49, v33
	v_mul_f32_e32 v49, v37, v60
	v_fmac_f32_e32 v49, v50, v34
	v_mul_f32_e32 v50, v37, v61
	s_waitcnt lgkmcnt(0)
	v_fmac_f32_e32 v91, v92, v98
	v_fmac_f32_e32 v50, v63, v35
	ds_read_b128 v[32:35], v68 offset:1600
	ds_read_b128 v[58:61], v68 offset:3648
	v_fmac_f32_e32 v91, v93, v62
	v_fmac_f32_e32 v91, v94, v49
	v_fmac_f32_e32 v91, v95, v50
	ds_read_b128 v[92:95], v68 offset:5696
	s_waitcnt lgkmcnt(1)
	v_mul_f32_e32 v63, v37, v58
	v_fmac_f32_e32 v63, v76, v32
	v_mul_f32_e32 v76, v37, v59
	v_fmac_f32_e32 v76, v78, v33
	v_mul_f32_e32 v78, v37, v60
	v_mul_f32_e32 v99, v37, v61
	s_waitcnt lgkmcnt(0)
	v_fmac_f32_e32 v91, v92, v63
	v_fmac_f32_e32 v78, v44, v34
	v_fmac_f32_e32 v99, v79, v35
	ds_read_b128 v[32:35], v68 offset:1616
	ds_read_b128 v[58:61], v68 offset:3664
	v_fmac_f32_e32 v91, v93, v76
	v_fmac_f32_e32 v91, v94, v78
	v_fmac_f32_e32 v91, v95, v99
	ds_read_b128 v[92:95], v68 offset:5712
	s_waitcnt lgkmcnt(1)
	v_mul_f32_e32 v79, v37, v58
	v_fmac_f32_e32 v79, v87, v32
	v_mul_f32_e32 v87, v37, v59
	v_fmac_f32_e32 v87, v38, v33
	v_mul_f32_e32 v38, v37, v60
	s_waitcnt lgkmcnt(0)
	v_fmac_f32_e32 v91, v92, v79
	v_fmac_f32_e32 v38, v39, v34
	v_mul_f32_e32 v39, v37, v61
	v_fmac_f32_e32 v91, v93, v87
	v_fmac_f32_e32 v39, v88, v35
	ds_read_b128 v[32:35], v68 offset:1632
	ds_read_b128 v[58:61], v68 offset:3680
	v_fmac_f32_e32 v91, v94, v38
	v_fmac_f32_e32 v91, v95, v39
	ds_read_b128 v[92:95], v68 offset:5728
	s_waitcnt lgkmcnt(1)
	v_mul_f32_e32 v88, v37, v58
	v_fmac_f32_e32 v88, v45, v32
	s_waitcnt lgkmcnt(0)
	v_fmac_f32_e32 v91, v92, v88
	v_mul_f32_e32 v92, v37, v59
	v_fmac_f32_e32 v92, v46, v33
	v_fmac_f32_e32 v91, v93, v92
	v_mul_f32_e32 v93, v37, v60
	v_fmac_f32_e32 v93, v47, v34
	v_fmac_f32_e32 v91, v94, v93
	v_mul_f32_e32 v94, v37, v61
	v_fmac_f32_e32 v94, v89, v35
	ds_read_b128 v[32:35], v68 offset:1648
	ds_read_b128 v[44:47], v68 offset:3696
	ds_read_b128 v[58:61], v68 offset:5744
	v_fmac_f32_e32 v91, v95, v94
	s_waitcnt lgkmcnt(1)
	v_mul_f32_e32 v44, v37, v44
	v_mul_f32_e32 v45, v37, v45
	v_fmac_f32_e32 v44, v90, v32
	v_fmac_f32_e32 v45, v40, v33
	v_mul_f32_e32 v40, v37, v46
	v_lshl_add_u64 v[32:33], v[70:71], 0, s[8:9]
	s_waitcnt lgkmcnt(0)
	v_fmac_f32_e32 v91, v58, v44
	v_fmac_f32_e32 v40, v41, v34
	v_mul_f32_e32 v41, v37, v47
	v_add_co_u32_e32 v34, vcc, s13, v32
	v_fmac_f32_e32 v91, v59, v45
	v_fmac_f32_e32 v41, v36, v35
	v_addc_co_u32_e32 v35, vcc, 0, v33, vcc
	v_fmac_f32_e32 v91, v60, v40
	v_add_co_u32_e32 v36, vcc, s70, v32
	v_fmac_f32_e32 v91, v61, v41
	s_nop 0
	v_addc_co_u32_e32 v37, vcc, 0, v33, vcc
	s_movk_i32 s8, 0x3000
	ds_write_b32 v86, v91 offset:9728
	global_store_dword v[32:33], v42, off nt
	global_store_dword v[32:33], v43, off offset:512 nt
	global_store_dword v[32:33], v52, off offset:1024 nt
	global_store_dword v[32:33], v53, off offset:1536 nt
	global_store_dword v[32:33], v54, off offset:2048 nt
	global_store_dword v[32:33], v55, off offset:2560 nt
	global_store_dword v[32:33], v51, off offset:3072 nt
	global_store_dword v[32:33], v48, off offset:3584 nt
	v_add_co_u32_e32 v32, vcc, s8, v32
	global_store_dword v[36:37], v56, off offset:-4096 nt
	global_store_dword v[34:35], v57, off offset:512 nt
	global_store_dword v[34:35], v96, off offset:1024 nt
	global_store_dword v[34:35], v97, off offset:1536 nt
	global_store_dword v[34:35], v98, off offset:2048 nt
	global_store_dword v[34:35], v62, off offset:2560 nt
	global_store_dword v[34:35], v49, off offset:3072 nt
	global_store_dword v[34:35], v50, off offset:3584 nt
	global_store_dword v[36:37], v63, off nt
	global_store_dword v[36:37], v76, off offset:512 nt
	global_store_dword v[36:37], v78, off offset:1024 nt
	global_store_dword v[36:37], v99, off offset:1536 nt
	global_store_dword v[36:37], v79, off offset:2048 nt
	global_store_dword v[36:37], v87, off offset:2560 nt
	global_store_dword v[36:37], v38, off offset:3072 nt
	global_store_dword v[36:37], v39, off offset:3584 nt
	v_addc_co_u32_e32 v33, vcc, 0, v33, vcc
	global_store_dword v[32:33], v88, off nt
	global_store_dword v[32:33], v92, off offset:512 nt
	global_store_dword v[32:33], v93, off offset:1024 nt
	global_store_dword v[32:33], v94, off offset:1536 nt
	global_store_dword v[32:33], v44, off offset:2048 nt
	global_store_dword v[32:33], v45, off offset:2560 nt
	global_store_dword v[32:33], v40, off offset:3072 nt
	global_store_dword v[32:33], v41, off offset:3584 nt
	s_waitcnt lgkmcnt(0)
	s_barrier
	ds_read_b32 v34, v84 offset:8192
	ds_read2st64_b32 v[32:33], v85 offset0:40 offset1:48
	s_waitcnt lgkmcnt(0)
	v_add_f32_e32 v32, v34, v32
	ds_read_b32 v34, v85 offset:14336
	s_waitcnt lgkmcnt(0)
	v_add_f32_e32 v33, v33, v34
	v_add_f32_e32 v32, v32, v33
	v_mul_f32_e32 v33, v32, v32
	ds_bpermute_b32 v33, v215, v33
	s_waitcnt lgkmcnt(0)
	v_fmac_f32_e32 v33, v32, v32
	ds_bpermute_b32 v34, v236, v33
	s_waitcnt lgkmcnt(0)
	v_add_f32_e32 v33, v33, v34
	ds_bpermute_b32 v34, v237, v33
	s_waitcnt lgkmcnt(0)
	v_add_f32_e32 v33, v33, v34
	ds_bpermute_b32 v34, v238, v33
	s_waitcnt lgkmcnt(0)
	v_add_f32_e32 v33, v33, v34
	ds_bpermute_b32 v34, v233, v33
	s_waitcnt lgkmcnt(0)
	v_add_f32_e32 v33, v33, v34
	ds_bpermute_b32 v34, v234, v33
	s_and_saveexec_b64 s[8:9], s[36:37]
	s_cbranch_execz .LBB0_559
	s_waitcnt lgkmcnt(0)
	v_add_f32_e32 v33, v33, v34
	ds_write_b32 v73, v33 offset:16384
	s_branch .LBB0_559
